# v046 + counted vmcnt ladder in the phase-4 FFN RMSNorm loop (matches the three sibling instances)
# speedup vs baseline: 1.0026x; 1.0026x over previous
; #define GAS __attribute__((address_space(1)))
; template <int MODE, bool XBF>
; __device__ __forceinline__ void rmsnorm_rows(const void* x, const float* gain, bf16_t* H, int gw, int NGW, int lane, const LAS float* WF, const float* fbias, float* LF) {
;     ...
;     for (int row0 = gw * RB; row0 < T; row0 += NGW * RB) {
;         f32x4 v[RB][2][2]; float s[RB];
; #pragma unroll
;         for (int r = 0; r < RB; ++r)
; #pragma unroll
;             for (int j = 0; j < 2; ++j) { const size_t xo = (size_t)(row0 + r) * D + 512 * j + lane * 8;
;                 if (XBF) unpack8h(*(const GAS u32x4*)((const bf16_t*)x + xo), v[r][j][0], v[r][j][1]);
;                 else { v[r][j][0] = *(const GAS f32x4*)((const float*)x + xo); v[r][j][1] = *(const GAS f32x4*)((const float*)x + xo + 4); } }
.LBB0_421:
	v_lshl_add_u64 v[18:19], s[28:29], 0, v[16:17]
	v_add_co_u32_e64 v36, s[2:3], s19, v18
	v_add_co_u32_e32 v30, vcc, 0x5800000, v18
	s_nop 0
	v_addc_co_u32_e64 v37, s[2:3], 0, v19, s[2:3]
	v_add_co_u32_e64 v38, s[2:3], s21, v18
	v_addc_co_u32_e32 v31, vcc, 0, v19, vcc
	s_nop 0
	v_addc_co_u32_e64 v39, s[2:3], 0, v19, s[2:3]
	v_add_co_u32_e64 v44, s[2:3], s23, v18
	v_lshl_add_u64 v[26:27], s[24:25], 0, v[16:17]
	s_nop 0
	v_addc_co_u32_e64 v45, s[2:3], 0, v19, s[2:3]
	global_load_dwordx4 v[32:35], v[38:39], off offset:-4096
	global_load_dwordx4 v[40:43], v[36:37], off offset:1024
	global_load_dwordx4 v[48:51], v[36:37], off offset:2048
	global_load_dwordx4 v[56:59], v[36:37], off offset:3072
	global_load_dwordx4 v[64:67], v[38:39], off
	global_load_dwordx4 v[72:75], v[38:39], off offset:1024
	global_load_dwordx4 v[80:83], v[38:39], off offset:2048
	global_load_dwordx4 v[88:91], v[38:39], off offset:3072
	global_load_dwordx4 v[96:99], v[44:45], off
	global_load_dwordx4 v[104:107], v[44:45], off offset:1024
	global_load_dwordx4 v[112:115], v[44:45], off offset:2048
	global_load_dwordx4 v[120:123], v[44:45], off offset:3072
	global_load_dwordx4 v[128:131], v[30:31], off
	global_load_dwordx4 v[136:139], v[30:31], off offset:1024
	global_load_dwordx4 v[144:147], v[30:31], off offset:2048
	global_load_dwordx4 v[152:155], v[30:31], off offset:3072
	v_add_co_u32_e64 v22, s[2:3], s35, v26
	v_mov_b64_e32 v[20:21], s[34:35]
	s_nop 0
	v_addc_co_u32_e64 v23, s[2:3], 0, v27, s[2:3]
	v_add_co_u32_e64 v24, s[2:3], s38, v26
	s_add_i32 s18, s18, s20
	s_nop 0
	v_addc_co_u32_e64 v25, s[2:3], 0, v27, s[2:3]
	v_add_co_u32_e64 v28, s[2:3], s39, v26
	s_add_u32 s24, s24, s26
	s_nop 0
	v_addc_co_u32_e64 v29, s[2:3], 0, v27, s[2:3]
	v_add_co_u32_e64 v26, s[2:3], s40, v26
	s_addc_u32 s25, s25, s27
	s_nop 0
	v_addc_co_u32_e64 v27, s[2:3], 0, v27, s[2:3]
	s_add_u32 s28, s28, s26
	s_addc_u32 s29, s29, s27
	s_cmp_lt_i32 s18, 0x8000
	s_waitcnt vmcnt(15)
	v_cvt_f32_f16_e32 v18, v32
	v_cvt_f32_f16_sdwa v19, v32 dst_sel:DWORD dst_unused:UNUSED_PAD src0_sel:WORD_1
	v_cvt_f32_f16_e32 v30, v33
	v_cvt_f32_f16_sdwa v31, v33 dst_sel:DWORD dst_unused:UNUSED_PAD src0_sel:WORD_1
	v_cvt_f32_f16_e32 v32, v34
	v_cvt_f32_f16_sdwa v33, v34 dst_sel:DWORD dst_unused:UNUSED_PAD src0_sel:WORD_1
	v_cvt_f32_f16_e32 v34, v35
	v_cvt_f32_f16_sdwa v35, v35 dst_sel:DWORD dst_unused:UNUSED_PAD src0_sel:WORD_1
	s_waitcnt vmcnt(14)
	v_cvt_f32_f16_e32 v36, v40
	v_cvt_f32_f16_sdwa v37, v40 dst_sel:DWORD dst_unused:UNUSED_PAD src0_sel:WORD_1
	v_cvt_f32_f16_e32 v40, v41
	s_waitcnt vmcnt(13)
	v_cvt_f32_f16_e32 v44, v48
	v_cvt_f32_f16_sdwa v45, v48 dst_sel:DWORD dst_unused:UNUSED_PAD src0_sel:WORD_1
	v_cvt_f32_f16_e32 v46, v49
	v_cvt_f32_f16_sdwa v47, v49 dst_sel:DWORD dst_unused:UNUSED_PAD src0_sel:WORD_1
	v_cvt_f32_f16_e32 v48, v50
	v_cvt_f32_f16_sdwa v49, v50 dst_sel:DWORD dst_unused:UNUSED_PAD src0_sel:WORD_1
	v_cvt_f32_f16_e32 v50, v51
	v_cvt_f32_f16_sdwa v51, v51 dst_sel:DWORD dst_unused:UNUSED_PAD src0_sel:WORD_1
	v_cvt_f32_f16_sdwa v41, v41 dst_sel:DWORD dst_unused:UNUSED_PAD src0_sel:WORD_1
	s_waitcnt vmcnt(12)
	v_cvt_f32_f16_e32 v52, v56
	v_cvt_f32_f16_sdwa v53, v56 dst_sel:DWORD dst_unused:UNUSED_PAD src0_sel:WORD_1
	v_cvt_f32_f16_e32 v56, v57
	s_waitcnt vmcnt(11)
	v_cvt_f32_f16_e32 v60, v64
	v_cvt_f32_f16_sdwa v61, v64 dst_sel:DWORD dst_unused:UNUSED_PAD src0_sel:WORD_1
	v_cvt_f32_f16_e32 v62, v65
	v_cvt_f32_f16_sdwa v63, v65 dst_sel:DWORD dst_unused:UNUSED_PAD src0_sel:WORD_1
	v_cvt_f32_f16_e32 v64, v66
	v_cvt_f32_f16_sdwa v65, v66 dst_sel:DWORD dst_unused:UNUSED_PAD src0_sel:WORD_1
	v_cvt_f32_f16_e32 v66, v67
	v_cvt_f32_f16_sdwa v67, v67 dst_sel:DWORD dst_unused:UNUSED_PAD src0_sel:WORD_1
	s_waitcnt vmcnt(10)
	v_cvt_f32_f16_e32 v68, v72
	v_cvt_f32_f16_sdwa v69, v72 dst_sel:DWORD dst_unused:UNUSED_PAD src0_sel:WORD_1
	v_cvt_f32_f16_e32 v72, v73
	s_waitcnt vmcnt(9)
	v_cvt_f32_f16_e32 v76, v80
	v_cvt_f32_f16_sdwa v77, v80 dst_sel:DWORD dst_unused:UNUSED_PAD src0_sel:WORD_1
	v_cvt_f32_f16_e32 v78, v81
	v_cvt_f32_f16_sdwa v79, v81 dst_sel:DWORD dst_unused:UNUSED_PAD src0_sel:WORD_1
	v_cvt_f32_f16_e32 v80, v82
	v_cvt_f32_f16_sdwa v81, v82 dst_sel:DWORD dst_unused:UNUSED_PAD src0_sel:WORD_1
	v_cvt_f32_f16_e32 v82, v83
	v_cvt_f32_f16_sdwa v83, v83 dst_sel:DWORD dst_unused:UNUSED_PAD src0_sel:WORD_1
	s_waitcnt vmcnt(8)
	v_cvt_f32_f16_e32 v84, v88
	v_cvt_f32_f16_sdwa v85, v88 dst_sel:DWORD dst_unused:UNUSED_PAD src0_sel:WORD_1
	v_cvt_f32_f16_e32 v88, v89
	s_waitcnt vmcnt(7)
	v_cvt_f32_f16_e32 v92, v96
	v_cvt_f32_f16_sdwa v93, v96 dst_sel:DWORD dst_unused:UNUSED_PAD src0_sel:WORD_1
	v_cvt_f32_f16_e32 v94, v97
	v_cvt_f32_f16_sdwa v95, v97 dst_sel:DWORD dst_unused:UNUSED_PAD src0_sel:WORD_1
	v_cvt_f32_f16_e32 v96, v98
	v_cvt_f32_f16_sdwa v97, v98 dst_sel:DWORD dst_unused:UNUSED_PAD src0_sel:WORD_1
	v_cvt_f32_f16_e32 v98, v99
	v_cvt_f32_f16_sdwa v99, v99 dst_sel:DWORD dst_unused:UNUSED_PAD src0_sel:WORD_1
	s_waitcnt vmcnt(5)
	v_cvt_f32_f16_e32 v108, v112
	v_cvt_f32_f16_sdwa v109, v112 dst_sel:DWORD dst_unused:UNUSED_PAD src0_sel:WORD_1
	v_cvt_f32_f16_e32 v110, v113
	v_cvt_f32_f16_sdwa v111, v113 dst_sel:DWORD dst_unused:UNUSED_PAD src0_sel:WORD_1
	v_cvt_f32_f16_e32 v112, v114
	v_cvt_f32_f16_sdwa v113, v114 dst_sel:DWORD dst_unused:UNUSED_PAD src0_sel:WORD_1
	v_cvt_f32_f16_e32 v114, v115
	v_cvt_f32_f16_sdwa v115, v115 dst_sel:DWORD dst_unused:UNUSED_PAD src0_sel:WORD_1
	s_waitcnt vmcnt(3)
; #define GAS __attribute__((address_space(1)))
; template <int MODE, bool XBF>
; __device__ __forceinline__ void rmsnorm_rows(const void* x, const float* gain, bf16_t* H, int gw, int NGW, int lane, const LAS float* WF, const float* fbias, float* LF) {
;     ...
;                 if (XBF) unpack8h(*(const GAS u32x4*)((const bf16_t*)x + xo), v[r][j][0], v[r][j][1]);
;                 else { v[r][j][0] = *(const GAS f32x4*)((const float*)x + xo); v[r][j][1] = *(const GAS f32x4*)((const float*)x + xo + 4); } }
; #pragma unroll
;         for (int r = 0; r < RB; ++r) { s[r] = 0.f;
; #pragma unroll
;             for (int j = 0; j < 2; ++j)
; #pragma unroll
;                 for (int e = 0; e < 2; ++e) s[r] += (v[r][j][e][0] * v[r][j][e][0] + v[r][j][e][1] * v[r][j][e][1]) + (v[r][j][e][2] * v[r][j][e][2] + v[r][j][e][3] * v[r][j][e][3]); }
	v_cvt_f32_f16_e32 v124, v128
	v_cvt_f32_f16_sdwa v125, v128 dst_sel:DWORD dst_unused:UNUSED_PAD src0_sel:WORD_1
	v_cvt_f32_f16_e32 v126, v129
	v_cvt_f32_f16_sdwa v127, v129 dst_sel:DWORD dst_unused:UNUSED_PAD src0_sel:WORD_1
	v_cvt_f32_f16_e32 v128, v130
	v_cvt_f32_f16_sdwa v129, v130 dst_sel:DWORD dst_unused:UNUSED_PAD src0_sel:WORD_1
	v_cvt_f32_f16_e32 v130, v131
	v_cvt_f32_f16_sdwa v131, v131 dst_sel:DWORD dst_unused:UNUSED_PAD src0_sel:WORD_1
	s_waitcnt vmcnt(1)
	v_cvt_f32_f16_e32 v140, v144
	v_cvt_f32_f16_sdwa v141, v144 dst_sel:DWORD dst_unused:UNUSED_PAD src0_sel:WORD_1
	v_cvt_f32_f16_e32 v142, v145
	v_cvt_f32_f16_sdwa v143, v145 dst_sel:DWORD dst_unused:UNUSED_PAD src0_sel:WORD_1
	v_cvt_f32_f16_e32 v144, v146
	v_cvt_f32_f16_sdwa v145, v146 dst_sel:DWORD dst_unused:UNUSED_PAD src0_sel:WORD_1
	v_cvt_f32_f16_e32 v146, v147
	v_cvt_f32_f16_sdwa v147, v147 dst_sel:DWORD dst_unused:UNUSED_PAD src0_sel:WORD_1
	v_cvt_f32_f16_sdwa v39, v43 dst_sel:DWORD dst_unused:UNUSED_PAD src0_sel:WORD_1
	v_cvt_f32_f16_e32 v38, v43
	v_cvt_f32_f16_sdwa v57, v57 dst_sel:DWORD dst_unused:UNUSED_PAD src0_sel:WORD_1
	v_cvt_f32_f16_sdwa v73, v73 dst_sel:DWORD dst_unused:UNUSED_PAD src0_sel:WORD_1
	v_cvt_f32_f16_sdwa v89, v89 dst_sel:DWORD dst_unused:UNUSED_PAD src0_sel:WORD_1
	v_cvt_f32_f16_sdwa v55, v59 dst_sel:DWORD dst_unused:UNUSED_PAD src0_sel:WORD_1
	v_cvt_f32_f16_e32 v54, v59
	v_cvt_f32_f16_sdwa v71, v75 dst_sel:DWORD dst_unused:UNUSED_PAD src0_sel:WORD_1
	v_cvt_f32_f16_e32 v70, v75
	v_cvt_f32_f16_sdwa v87, v91 dst_sel:DWORD dst_unused:UNUSED_PAD src0_sel:WORD_1
	v_cvt_f32_f16_e32 v86, v91
	v_cvt_f32_f16_e32 v100, v104
	v_cvt_f32_f16_sdwa v101, v104 dst_sel:DWORD dst_unused:UNUSED_PAD src0_sel:WORD_1
	v_cvt_f32_f16_e32 v104, v105
	v_cvt_f32_f16_e32 v116, v120
	v_cvt_f32_f16_sdwa v117, v120 dst_sel:DWORD dst_unused:UNUSED_PAD src0_sel:WORD_1
	v_cvt_f32_f16_e32 v120, v121
	v_cvt_f32_f16_e32 v132, v136
	v_cvt_f32_f16_sdwa v133, v136 dst_sel:DWORD dst_unused:UNUSED_PAD src0_sel:WORD_1
	v_cvt_f32_f16_e32 v136, v137
	s_waitcnt vmcnt(0)
	v_cvt_f32_f16_e32 v148, v152
	v_cvt_f32_f16_sdwa v149, v152 dst_sel:DWORD dst_unused:UNUSED_PAD src0_sel:WORD_1
	v_cvt_f32_f16_e32 v152, v153
	v_cvt_f32_f16_sdwa v43, v42 dst_sel:DWORD dst_unused:UNUSED_PAD src0_sel:WORD_1
	v_cvt_f32_f16_e32 v42, v42
	v_cvt_f32_f16_sdwa v59, v58 dst_sel:DWORD dst_unused:UNUSED_PAD src0_sel:WORD_1
	v_cvt_f32_f16_e32 v58, v58
	v_cvt_f32_f16_sdwa v105, v105 dst_sel:DWORD dst_unused:UNUSED_PAD src0_sel:WORD_1
	v_cvt_f32_f16_sdwa v121, v121 dst_sel:DWORD dst_unused:UNUSED_PAD src0_sel:WORD_1
	v_cvt_f32_f16_sdwa v137, v137 dst_sel:DWORD dst_unused:UNUSED_PAD src0_sel:WORD_1
	v_cvt_f32_f16_sdwa v153, v153 dst_sel:DWORD dst_unused:UNUSED_PAD src0_sel:WORD_1
	v_pk_mul_f32 v[164:165], v[30:31], v[30:31]
	v_pk_mul_f32 v[166:167], v[18:19], v[18:19]
	v_pk_mul_f32 v[168:169], v[34:35], v[34:35]
	v_pk_mul_f32 v[170:171], v[32:33], v[32:33]
	v_mul_f32_e32 v172, v36, v36
	v_mul_f32_e32 v174, v40, v40
	v_pk_mul_f32 v[176:177], v[46:47], v[46:47]
	v_pk_mul_f32 v[178:179], v[44:45], v[44:45]
	v_pk_mul_f32 v[180:181], v[50:51], v[50:51]
	v_pk_mul_f32 v[182:183], v[48:49], v[48:49]
	v_cvt_f32_f16_sdwa v75, v74 dst_sel:DWORD dst_unused:UNUSED_PAD src0_sel:WORD_1
	v_cvt_f32_f16_e32 v74, v74
	v_cvt_f32_f16_sdwa v91, v90 dst_sel:DWORD dst_unused:UNUSED_PAD src0_sel:WORD_1
	v_cvt_f32_f16_e32 v90, v90
	v_cvt_f32_f16_sdwa v103, v107 dst_sel:DWORD dst_unused:UNUSED_PAD src0_sel:WORD_1
	v_cvt_f32_f16_e32 v102, v107
	v_cvt_f32_f16_sdwa v107, v106 dst_sel:DWORD dst_unused:UNUSED_PAD src0_sel:WORD_1
	v_cvt_f32_f16_e32 v106, v106
	v_cvt_f32_f16_sdwa v119, v123 dst_sel:DWORD dst_unused:UNUSED_PAD src0_sel:WORD_1
	v_cvt_f32_f16_e32 v118, v123
	v_cvt_f32_f16_sdwa v123, v122 dst_sel:DWORD dst_unused:UNUSED_PAD src0_sel:WORD_1
	v_cvt_f32_f16_e32 v122, v122
	v_cvt_f32_f16_sdwa v135, v139 dst_sel:DWORD dst_unused:UNUSED_PAD src0_sel:WORD_1
	v_cvt_f32_f16_e32 v134, v139
	v_cvt_f32_f16_sdwa v139, v138 dst_sel:DWORD dst_unused:UNUSED_PAD src0_sel:WORD_1
	v_cvt_f32_f16_e32 v138, v138
	v_cvt_f32_f16_sdwa v151, v155 dst_sel:DWORD dst_unused:UNUSED_PAD src0_sel:WORD_1
	v_cvt_f32_f16_e32 v150, v155
	v_cvt_f32_f16_sdwa v155, v154 dst_sel:DWORD dst_unused:UNUSED_PAD src0_sel:WORD_1
	v_cvt_f32_f16_e32 v154, v154
	v_mul_f32_e32 v184, v52, v52
	v_mul_f32_e32 v186, v56, v56
	v_pk_mul_f32 v[188:189], v[62:63], v[62:63]
	v_pk_mul_f32 v[190:191], v[60:61], v[60:61]
	v_pk_mul_f32 v[192:193], v[66:67], v[66:67]
	v_pk_mul_f32 v[194:195], v[64:65], v[64:65]
	v_mul_f32_e32 v196, v68, v68
	v_mul_f32_e32 v198, v72, v72
	v_pk_mul_f32 v[200:201], v[78:79], v[78:79]
	v_pk_mul_f32 v[202:203], v[76:77], v[76:77]
	v_pk_mul_f32 v[206:207], v[82:83], v[82:83]
	v_pk_mul_f32 v[208:209], v[80:81], v[80:81]
	v_mul_f32_e32 v210, v84, v84
	v_mul_f32_e32 v212, v88, v88
	v_pk_mul_f32 v[214:215], v[94:95], v[94:95]
	v_pk_mul_f32 v[216:217], v[92:93], v[92:93]
	v_pk_mul_f32 v[218:219], v[98:99], v[98:99]
	v_pk_mul_f32 v[220:221], v[96:97], v[96:97]
	v_pk_mul_f32 v[226:227], v[110:111], v[110:111]
	v_pk_mul_f32 v[228:229], v[108:109], v[108:109]
	v_pk_mul_f32 v[230:231], v[114:115], v[114:115]
	v_pk_mul_f32 v[232:233], v[112:113], v[112:113]
	v_pk_mul_f32 v[238:239], v[126:127], v[126:127]
	v_pk_mul_f32 v[240:241], v[124:125], v[124:125]
	v_pk_mul_f32 v[242:243], v[130:131], v[130:131]
	v_pk_mul_f32 v[244:245], v[128:129], v[128:129]
	v_pk_mul_f32 v[246:247], v[142:143], v[142:143]
	v_pk_mul_f32 v[248:249], v[140:141], v[140:141]
	v_pk_mul_f32 v[250:251], v[146:147], v[146:147]
	v_pk_mul_f32 v[252:253], v[144:145], v[144:145]
	v_pk_mov_b32 v[204:205], v[166:167], v[164:165] op_sel:[1,0]
; template <int MODE, bool XBF>
; __device__ __forceinline__ void rmsnorm_rows(const void* x, const float* gain, bf16_t* H, int gw, int NGW, int lane, const LAS float* WF, const float* fbias, float* LF) {
;     ...
;         for (int r = 0; r < RB; ++r) { s[r] = 0.f;
; #pragma unroll
;             for (int j = 0; j < 2; ++j)
; #pragma unroll
;                 for (int e = 0; e < 2; ++e) s[r] += (v[r][j][e][0] * v[r][j][e][0] + v[r][j][e][1] * v[r][j][e][1]) + (v[r][j][e][2] * v[r][j][e][2] + v[r][j][e][3] * v[r][j][e][3]); }
	v_mov_b32_e32 v167, v165
	v_pk_mov_b32 v[164:165], v[170:171], v[168:169] op_sel:[1,0]
	v_mov_b32_e32 v171, v169
	v_pk_mov_b32 v[168:169], v[178:179], v[176:177] op_sel:[1,0]
	v_mov_b32_e32 v179, v177
	v_pk_mov_b32 v[176:177], v[182:183], v[180:181] op_sel:[1,0]
	v_mov_b32_e32 v183, v181
	v_pk_fma_f32 v[172:173], v[36:37], v[36:37], v[172:173] op_sel_hi:[1,1,0]
	v_pk_fma_f32 v[174:175], v[40:41], v[40:41], v[174:175] op_sel_hi:[1,1,0]
	v_pk_mov_b32 v[180:181], v[190:191], v[188:189] op_sel:[1,0]
	v_mov_b32_e32 v191, v189
	v_pk_mov_b32 v[188:189], v[194:195], v[192:193] op_sel:[1,0]
	v_mov_b32_e32 v195, v193
	v_pk_mov_b32 v[192:193], v[202:203], v[200:201] op_sel:[1,0]
	v_mov_b32_e32 v203, v201
	v_pk_mov_b32 v[200:201], v[208:209], v[206:207] op_sel:[1,0]
	v_mov_b32_e32 v209, v207
	v_pk_mov_b32 v[206:207], v[216:217], v[214:215] op_sel:[1,0]
	v_mov_b32_e32 v217, v215
	v_pk_mov_b32 v[214:215], v[220:221], v[218:219] op_sel:[1,0]
	v_mov_b32_e32 v221, v219
	v_pk_mov_b32 v[218:219], v[228:229], v[226:227] op_sel:[1,0]
	v_mov_b32_e32 v229, v227
	v_pk_mov_b32 v[226:227], v[232:233], v[230:231] op_sel:[1,0]
	v_mov_b32_e32 v233, v231
	v_pk_mov_b32 v[230:231], v[240:241], v[238:239] op_sel:[1,0]
	v_mov_b32_e32 v241, v239
	v_pk_mov_b32 v[238:239], v[244:245], v[242:243] op_sel:[1,0]
	v_mov_b32_e32 v245, v243
	v_pk_mov_b32 v[242:243], v[248:249], v[246:247] op_sel:[1,0]
	v_mov_b32_e32 v249, v247
	v_pk_mov_b32 v[246:247], v[252:253], v[250:251] op_sel:[1,0]
	v_mov_b32_e32 v253, v251
	v_pk_add_f32 v[166:167], v[204:205], v[166:167]
	v_pk_add_f32 v[164:165], v[164:165], v[170:171]
	v_pk_add_f32 v[168:169], v[168:169], v[178:179]
	v_pk_fma_f32 v[184:185], v[52:53], v[52:53], v[184:185] op_sel_hi:[1,1,0]
	v_pk_fma_f32 v[186:187], v[56:57], v[56:57], v[186:187] op_sel_hi:[1,1,0]
	v_pk_fma_f32 v[196:197], v[68:69], v[68:69], v[196:197] op_sel_hi:[1,1,0]
	v_pk_fma_f32 v[198:199], v[72:73], v[72:73], v[198:199] op_sel_hi:[1,1,0]
	v_pk_fma_f32 v[210:211], v[84:85], v[84:85], v[210:211] op_sel_hi:[1,1,0]
	v_pk_fma_f32 v[212:213], v[88:89], v[88:89], v[212:213] op_sel_hi:[1,1,0]
	v_mul_f32_e32 v172, v38, v38
	v_mul_f32_e32 v174, v39, v39
	v_pk_add_f32 v[176:177], v[176:177], v[182:183]
	v_mul_f32_e32 v222, v100, v100
	v_mul_f32_e32 v224, v104, v104
	v_mul_f32_e32 v234, v116, v116
	v_mul_f32_e32 v236, v120, v120
	v_mul_f32_e32 v250, v132, v132
	v_mul_f32_e32 v204, v136, v136
	v_mul_f32_e32 v170, v148, v148
	v_mul_f32_e32 v178, v152, v152
	v_mul_f32_e32 v184, v54, v54
	v_mul_f32_e32 v186, v55, v55
	v_pk_add_f32 v[180:181], v[180:181], v[190:191]
	v_pk_add_f32 v[182:183], v[188:189], v[194:195]
	v_mul_f32_e32 v196, v70, v70
	v_mul_f32_e32 v198, v71, v71
	v_pk_add_f32 v[188:189], v[192:193], v[202:203]
	v_pk_add_f32 v[190:191], v[200:201], v[208:209]
	v_mul_f32_e32 v210, v86, v86
	v_mul_f32_e32 v212, v87, v87
	v_pk_add_f32 v[192:193], v[206:207], v[216:217]
	v_pk_add_f32 v[194:195], v[214:215], v[220:221]
	v_pk_add_f32 v[200:201], v[218:219], v[228:229]
	v_pk_add_f32 v[202:203], v[226:227], v[232:233]
	v_pk_add_f32 v[206:207], v[230:231], v[240:241]
	v_pk_add_f32 v[208:209], v[238:239], v[244:245]
	v_pk_add_f32 v[214:215], v[242:243], v[248:249]
	v_pk_add_f32 v[216:217], v[246:247], v[252:253]
	v_pk_add_f32 v[166:167], v[166:167], v[166:167] op_sel_hi:[0,1]
	v_pk_add_f32 v[164:165], v[164:165], v[164:165] op_sel_hi:[0,1]
	v_pk_add_f32 v[172:173], v[172:173], v[174:175]
	v_pk_add_f32 v[168:169], v[168:169], v[168:169] op_sel_hi:[0,1]
	v_pk_add_f32 v[174:175], v[176:177], v[176:177] op_sel_hi:[0,1]
	v_pk_fma_f32 v[222:223], v[100:101], v[100:101], v[222:223] op_sel_hi:[1,1,0]
	v_pk_fma_f32 v[224:225], v[104:105], v[104:105], v[224:225] op_sel_hi:[1,1,0]
	v_pk_fma_f32 v[234:235], v[116:117], v[116:117], v[234:235] op_sel_hi:[1,1,0]
	v_pk_fma_f32 v[236:237], v[120:121], v[120:121], v[236:237] op_sel_hi:[1,1,0]
	v_pk_fma_f32 v[250:251], v[132:133], v[132:133], v[250:251] op_sel_hi:[1,1,0]
	v_pk_fma_f32 v[204:205], v[136:137], v[136:137], v[204:205] op_sel_hi:[1,1,0]
	v_pk_fma_f32 v[170:171], v[148:149], v[148:149], v[170:171] op_sel_hi:[1,1,0]
	v_pk_fma_f32 v[178:179], v[152:153], v[152:153], v[178:179] op_sel_hi:[1,1,0]
	v_pk_add_f32 v[176:177], v[184:185], v[186:187]
	v_pk_add_f32 v[180:181], v[180:181], v[180:181] op_sel_hi:[0,1]
	v_pk_add_f32 v[182:183], v[182:183], v[182:183] op_sel_hi:[0,1]
	v_pk_add_f32 v[184:185], v[196:197], v[198:199]
	v_pk_add_f32 v[186:187], v[188:189], v[188:189] op_sel_hi:[0,1]
	v_pk_add_f32 v[188:189], v[190:191], v[190:191] op_sel_hi:[0,1]
	v_pk_add_f32 v[190:191], v[210:211], v[212:213]
	v_pk_add_f32 v[192:193], v[192:193], v[192:193] op_sel_hi:[0,1]
	v_pk_add_f32 v[194:195], v[194:195], v[194:195] op_sel_hi:[0,1]
	v_pk_add_f32 v[198:199], v[200:201], v[200:201] op_sel_hi:[0,1]
	v_pk_add_f32 v[200:201], v[202:203], v[202:203] op_sel_hi:[0,1]
	v_pk_add_f32 v[206:207], v[206:207], v[206:207] op_sel_hi:[0,1]
	v_pk_add_f32 v[208:209], v[208:209], v[208:209] op_sel_hi:[0,1]
	v_pk_add_f32 v[210:211], v[214:215], v[214:215] op_sel_hi:[0,1]
	v_pk_add_f32 v[212:213], v[216:217], v[216:217] op_sel_hi:[0,1]
	v_mul_f32_e32 v166, v42, v42
	v_mul_f32_e32 v164, v43, v43
	v_mul_f32_e32 v168, v58, v58
	v_mul_f32_e32 v174, v59, v59
	v_mul_f32_e32 v222, v102, v102
	v_mul_f32_e32 v224, v103, v103
	v_mul_f32_e32 v234, v118, v118
	v_mul_f32_e32 v236, v119, v119
	v_mul_f32_e32 v250, v134, v134
	v_mul_f32_e32 v204, v135, v135
	v_mul_f32_e32 v170, v150, v150
	v_mul_f32_e32 v178, v151, v151
	v_mul_f32_e32 v180, v74, v74
	v_mul_f32_e32 v182, v75, v75
	v_mul_f32_e32 v186, v90, v90
	v_mul_f32_e32 v188, v91, v91
	v_mul_f32_e32 v192, v106, v106
	v_mul_f32_e32 v194, v107, v107
; template <int MODE, bool XBF>
; __device__ __forceinline__ void rmsnorm_rows(const void* x, const float* gain, bf16_t* H, int gw, int NGW, int lane, const LAS float* WF, const float* fbias, float* LF) {
;     ...
;         for (int r = 0; r < RB; ++r) { s[r] = 0.f;
; #pragma unroll
;             for (int j = 0; j < 2; ++j)
; #pragma unroll
;                 for (int e = 0; e < 2; ++e) s[r] += (v[r][j][e][0] * v[r][j][e][0] + v[r][j][e][1] * v[r][j][e][1]) + (v[r][j][e][2] * v[r][j][e][2] + v[r][j][e][3] * v[r][j][e][3]); }
; #pragma unroll
;         for (int o = 1; o < 64; o <<= 1)
; #pragma unroll
;             for (int r = 0; r < RB; ++r) s[r] += __shfl_xor(s[r], o);
	v_mul_f32_e32 v198, v122, v122
	v_mul_f32_e32 v200, v123, v123
	v_mul_f32_e32 v206, v138, v138
	v_mul_f32_e32 v208, v139, v139
	v_mul_f32_e32 v210, v154, v154
	v_mul_f32_e32 v212, v155, v155
	v_pk_add_f32 v[164:165], v[166:167], v[164:165]
	v_pk_add_f32 v[166:167], v[168:169], v[174:175]
	v_pk_add_f32 v[196:197], v[222:223], v[224:225]
	v_pk_add_f32 v[202:203], v[234:235], v[236:237]
	v_pk_add_f32 v[204:205], v[250:251], v[204:205]
	v_pk_add_f32 v[170:171], v[170:171], v[178:179]
	v_pk_add_f32 v[168:169], v[180:181], v[182:183]
	v_pk_add_f32 v[174:175], v[186:187], v[188:189]
	v_pk_add_f32 v[178:179], v[192:193], v[194:195]
	v_pk_add_f32 v[180:181], v[198:199], v[200:201]
	v_pk_add_f32 v[182:183], v[206:207], v[208:209]
	v_pk_add_f32 v[186:187], v[210:211], v[212:213]
	v_pk_add_f32 v[164:165], v[164:165], v[172:173]
	v_pk_add_f32 v[166:167], v[166:167], v[176:177]
	v_pk_add_f32 v[168:169], v[168:169], v[184:185]
	v_pk_add_f32 v[172:173], v[174:175], v[190:191]
	v_pk_add_f32 v[174:175], v[178:179], v[196:197]
	v_pk_add_f32 v[176:177], v[180:181], v[202:203]
	v_pk_add_f32 v[178:179], v[182:183], v[204:205]
	v_pk_add_f32 v[170:171], v[186:187], v[170:171]
	v_mov_b32_e32 v180, v166
	v_mov_b32_e32 v181, v164
	v_mov_b32_e32 v164, v167
	v_mov_b32_e32 v166, v172
	v_mov_b32_e32 v167, v168
	v_mov_b32_e32 v168, v173
	v_mov_b32_e32 v172, v176
	v_mov_b32_e32 v173, v174
	v_mov_b32_e32 v174, v177
	v_mov_b32_e32 v176, v170
	v_mov_b32_e32 v177, v178
	v_mov_b32_e32 v178, v171
	v_pk_add_f32 v[164:165], v[180:181], v[164:165]
	v_pk_add_f32 v[166:167], v[166:167], v[168:169]
	v_pk_add_f32 v[168:169], v[172:173], v[174:175]
	v_pk_add_f32 v[170:171], v[176:177], v[178:179]
	ds_bpermute_b32 v173, v157, v165
	ds_bpermute_b32 v172, v157, v164
	ds_bpermute_b32 v175, v157, v167
	ds_bpermute_b32 v174, v157, v166
	ds_bpermute_b32 v177, v157, v169
	ds_bpermute_b32 v176, v157, v168
	ds_bpermute_b32 v179, v157, v171
	ds_bpermute_b32 v178, v157, v170
	s_waitcnt lgkmcnt(6)
	v_pk_add_f32 v[164:165], v[164:165], v[172:173]
	s_waitcnt lgkmcnt(4)
	v_pk_add_f32 v[166:167], v[166:167], v[174:175]
	s_waitcnt lgkmcnt(2)
	v_pk_add_f32 v[168:169], v[168:169], v[176:177]
	ds_bpermute_b32 v173, v158, v165
	s_waitcnt lgkmcnt(1)
	v_pk_add_f32 v[170:171], v[170:171], v[178:179]
	ds_bpermute_b32 v172, v158, v164
	ds_bpermute_b32 v175, v158, v167
	ds_bpermute_b32 v174, v158, v166
	ds_bpermute_b32 v177, v158, v169
	ds_bpermute_b32 v176, v158, v168
	ds_bpermute_b32 v179, v158, v171
	ds_bpermute_b32 v178, v158, v170
	s_waitcnt lgkmcnt(6)
	v_pk_add_f32 v[164:165], v[164:165], v[172:173]
	s_waitcnt lgkmcnt(4)
	v_pk_add_f32 v[166:167], v[166:167], v[174:175]
	s_waitcnt lgkmcnt(2)
	v_pk_add_f32 v[168:169], v[168:169], v[176:177]
	ds_bpermute_b32 v173, v159, v165
	s_waitcnt lgkmcnt(1)
	v_pk_add_f32 v[170:171], v[170:171], v[178:179]
	ds_bpermute_b32 v172, v159, v164
	ds_bpermute_b32 v175, v159, v167
	ds_bpermute_b32 v174, v159, v166
	ds_bpermute_b32 v177, v159, v169
	ds_bpermute_b32 v176, v159, v168
	ds_bpermute_b32 v179, v159, v171
	ds_bpermute_b32 v178, v159, v170
	s_waitcnt lgkmcnt(6)
	v_pk_add_f32 v[164:165], v[164:165], v[172:173]
	s_waitcnt lgkmcnt(4)
	v_pk_add_f32 v[166:167], v[166:167], v[174:175]
	s_waitcnt lgkmcnt(2)
	v_pk_add_f32 v[168:169], v[168:169], v[176:177]
	ds_bpermute_b32 v173, v160, v165
	s_waitcnt lgkmcnt(1)
	v_pk_add_f32 v[170:171], v[170:171], v[178:179]
	ds_bpermute_b32 v172, v160, v164
	ds_bpermute_b32 v175, v160, v167
	ds_bpermute_b32 v174, v160, v166
	ds_bpermute_b32 v177, v160, v169
	ds_bpermute_b32 v176, v160, v168
	ds_bpermute_b32 v179, v160, v171
	ds_bpermute_b32 v178, v160, v170
	s_waitcnt lgkmcnt(6)
	v_pk_add_f32 v[164:165], v[164:165], v[172:173]
	s_waitcnt lgkmcnt(4)
	v_pk_add_f32 v[166:167], v[166:167], v[174:175]
	s_waitcnt lgkmcnt(2)
	v_pk_add_f32 v[168:169], v[168:169], v[176:177]
	ds_bpermute_b32 v173, v161, v165
	s_waitcnt lgkmcnt(1)
	v_pk_add_f32 v[170:171], v[170:171], v[178:179]
	ds_bpermute_b32 v172, v161, v164
	ds_bpermute_b32 v175, v161, v167
	ds_bpermute_b32 v174, v161, v166
	ds_bpermute_b32 v177, v161, v169
	ds_bpermute_b32 v176, v161, v168
	ds_bpermute_b32 v179, v161, v171
	ds_bpermute_b32 v178, v161, v170
	s_waitcnt lgkmcnt(6)
	v_pk_add_f32 v[164:165], v[164:165], v[172:173]
	s_waitcnt lgkmcnt(4)
	v_pk_add_f32 v[166:167], v[166:167], v[174:175]
	s_waitcnt lgkmcnt(2)
	v_pk_add_f32 v[168:169], v[168:169], v[176:177]
	ds_bpermute_b32 v173, v162, v165
	s_waitcnt lgkmcnt(1)
	v_pk_add_f32 v[170:171], v[170:171], v[178:179]
	ds_bpermute_b32 v172, v162, v164
	ds_bpermute_b32 v175, v162, v167
	ds_bpermute_b32 v174, v162, v166
	ds_bpermute_b32 v177, v162, v169
	ds_bpermute_b32 v176, v162, v168
	ds_bpermute_b32 v179, v162, v171
	ds_bpermute_b32 v178, v162, v170
	s_waitcnt lgkmcnt(6)
	v_pk_add_f32 v[164:165], v[164:165], v[172:173]
	s_waitcnt lgkmcnt(4)
	v_pk_add_f32 v[166:167], v[166:167], v[174:175]
	s_waitcnt lgkmcnt(2)
	v_pk_add_f32 v[168:169], v[168:169], v[176:177]
	v_pk_fma_f32 v[164:165], v[164:165], s[30:31], v[20:21] op_sel_hi:[1,0,0]
	s_waitcnt lgkmcnt(0)
; template <int MODE, bool XBF>
; __device__ __forceinline__ void rmsnorm_rows(const void* x, const float* gain, bf16_t* H, int gw, int NGW, int lane, const LAS float* WF, const float* fbias, float* LF) {
;     ...
;         for (int r = 0; r < RB; ++r) {
;             const int row = row0 + r;
;             const float rstd = rsqrtf(s[r] * (1.f / D) + 1e-6f);
;             const size_t hrow = MODE == 2 ? (size_t)row + (row >> 12) + 1 : (size_t)row;
; #pragma unroll
;             for (int j = 0; j < 2; ++j) { v[r][j][0] = v[r][j][0] * rstd * g[j][0]; v[r][j][1] = v[r][j][1] * rstd * g[j][1];
	v_pk_add_f32 v[170:171], v[170:171], v[178:179]
	v_pk_fma_f32 v[166:167], v[166:167], s[30:31], v[20:21] op_sel_hi:[1,0,0]
	v_pk_fma_f32 v[168:169], v[168:169], s[30:31], v[20:21] op_sel_hi:[1,0,0]
	v_pk_fma_f32 v[20:21], v[170:171], s[30:31], v[20:21] op_sel_hi:[1,0,0]
	v_mul_f32_e32 v163, 0x4b800000, v165
	v_cmp_gt_f32_e64 s[2:3], s31, v165
	v_mul_f32_e32 v170, 0x4b800000, v164
	v_cmp_gt_f32_e32 vcc, s31, v164
	v_mul_f32_e32 v171, 0x4b800000, v167
	v_mul_f32_e32 v172, 0x4b800000, v166
	v_cmp_gt_f32_e64 s[4:5], s31, v166
	v_cmp_gt_f32_e64 s[6:7], s31, v167
	v_mul_f32_e32 v173, 0x4b800000, v169
	v_mul_f32_e32 v174, 0x4b800000, v168
	v_cmp_gt_f32_e64 s[8:9], s31, v168
	v_cmp_gt_f32_e64 s[10:11], s31, v169
	v_mul_f32_e32 v175, 0x4b800000, v21
	v_mul_f32_e32 v176, 0x4b800000, v20
	v_cmp_gt_f32_e64 s[12:13], s31, v20
	v_cndmask_b32_e64 v163, v165, v163, s[2:3]
	v_cmp_gt_f32_e64 s[14:15], s31, v21
	v_cndmask_b32_e32 v164, v164, v170, vcc
	v_cndmask_b32_e64 v165, v167, v171, s[6:7]
	v_cndmask_b32_e64 v166, v166, v172, s[4:5]
	v_cndmask_b32_e64 v167, v169, v173, s[10:11]
	v_cndmask_b32_e64 v168, v168, v174, s[8:9]
	v_cndmask_b32_e64 v21, v21, v175, s[14:15]
	v_cndmask_b32_e64 v20, v20, v176, s[12:13]
	v_rsq_f32_e32 v163, v163
	v_rsq_f32_e32 v164, v164
	v_rsq_f32_e32 v165, v165
	v_rsq_f32_e32 v169, v166
	v_rsq_f32_e32 v167, v167
	v_rsq_f32_e32 v171, v168
	v_rsq_f32_e32 v21, v21
	v_rsq_f32_e32 v173, v20
	v_mul_f32_e32 v20, 0x45800000, v163
	v_mul_f32_e32 v166, 0x45800000, v164
	v_mul_f32_e32 v168, 0x45800000, v165
	v_mul_f32_e32 v170, 0x45800000, v169
	v_mul_f32_e32 v172, 0x45800000, v167
	v_mul_f32_e32 v174, 0x45800000, v171
	v_mul_f32_e32 v175, 0x45800000, v21
	v_mul_f32_e32 v176, 0x45800000, v173
	v_cndmask_b32_e64 v20, v163, v20, s[2:3]
	v_cndmask_b32_e32 v164, v164, v166, vcc
	v_cndmask_b32_e64 v166, v165, v168, s[6:7]
	v_cndmask_b32_e64 v168, v169, v170, s[4:5]
	v_cndmask_b32_e64 v170, v167, v172, s[10:11]
	v_cndmask_b32_e64 v172, v171, v174, s[8:9]
	v_cndmask_b32_e64 v174, v21, v175, s[14:15]
	v_cndmask_b32_e64 v176, v173, v176, s[12:13]
	v_pk_mul_f32 v[18:19], v[20:21], v[18:19] op_sel_hi:[0,1]
	v_pk_mul_f32 v[30:31], v[20:21], v[30:31] op_sel_hi:[0,1]
	v_pk_mul_f32 v[32:33], v[20:21], v[32:33] op_sel_hi:[0,1]
	v_pk_mul_f32 v[34:35], v[20:21], v[34:35] op_sel_hi:[0,1]
	v_pk_mul_f32 v[36:37], v[20:21], v[36:37] op_sel_hi:[0,1]
	v_pk_mul_f32 v[40:41], v[20:21], v[40:41] op_sel_hi:[0,1]
	v_pk_mul_f32 v[42:43], v[20:21], v[42:43] op_sel_hi:[0,1]
	v_pk_mul_f32 v[20:21], v[20:21], v[38:39] op_sel_hi:[0,1]
	v_pk_mul_f32 v[38:39], v[164:165], v[44:45] op_sel_hi:[0,1]
	v_pk_mul_f32 v[44:45], v[164:165], v[46:47] op_sel_hi:[0,1]
	v_pk_mul_f32 v[46:47], v[164:165], v[48:49] op_sel_hi:[0,1]
	v_pk_mul_f32 v[48:49], v[164:165], v[50:51] op_sel_hi:[0,1]
	v_pk_mul_f32 v[50:51], v[164:165], v[52:53] op_sel_hi:[0,1]
	v_pk_mul_f32 v[52:53], v[164:165], v[56:57] op_sel_hi:[0,1]
	v_pk_mul_f32 v[56:57], v[164:165], v[58:59] op_sel_hi:[0,1]
	v_pk_mul_f32 v[54:55], v[164:165], v[54:55] op_sel_hi:[0,1]
	v_pk_mul_f32 v[58:59], v[166:167], v[60:61] op_sel_hi:[0,1]
	v_pk_mul_f32 v[60:61], v[166:167], v[62:63] op_sel_hi:[0,1]
	v_pk_mul_f32 v[62:63], v[166:167], v[64:65] op_sel_hi:[0,1]
	v_pk_mul_f32 v[64:65], v[166:167], v[66:67] op_sel_hi:[0,1]
	v_pk_mul_f32 v[66:67], v[166:167], v[68:69] op_sel_hi:[0,1]
	v_pk_mul_f32 v[68:69], v[166:167], v[72:73] op_sel_hi:[0,1]
	v_pk_mul_f32 v[72:73], v[166:167], v[74:75] op_sel_hi:[0,1]
	v_pk_mul_f32 v[70:71], v[166:167], v[70:71] op_sel_hi:[0,1]
	v_pk_mul_f32 v[74:75], v[168:169], v[76:77] op_sel_hi:[0,1]
	v_pk_mul_f32 v[76:77], v[168:169], v[78:79] op_sel_hi:[0,1]
	v_pk_mul_f32 v[78:79], v[168:169], v[80:81] op_sel_hi:[0,1]
	v_pk_mul_f32 v[80:81], v[168:169], v[82:83] op_sel_hi:[0,1]
	v_pk_mul_f32 v[82:83], v[168:169], v[84:85] op_sel_hi:[0,1]
	v_pk_mul_f32 v[84:85], v[168:169], v[88:89] op_sel_hi:[0,1]
	v_pk_mul_f32 v[88:89], v[168:169], v[90:91] op_sel_hi:[0,1]
	v_pk_mul_f32 v[86:87], v[168:169], v[86:87] op_sel_hi:[0,1]
	v_pk_mul_f32 v[90:91], v[170:171], v[92:93] op_sel_hi:[0,1]
	v_pk_mul_f32 v[92:93], v[170:171], v[94:95] op_sel_hi:[0,1]
	v_pk_mul_f32 v[94:95], v[170:171], v[96:97] op_sel_hi:[0,1]
	v_pk_mul_f32 v[96:97], v[170:171], v[98:99] op_sel_hi:[0,1]
	v_pk_mul_f32 v[98:99], v[170:171], v[100:101] op_sel_hi:[0,1]
	v_pk_mul_f32 v[100:101], v[170:171], v[104:105] op_sel_hi:[0,1]
	v_pk_mul_f32 v[104:105], v[170:171], v[106:107] op_sel_hi:[0,1]
	v_pk_mul_f32 v[102:103], v[170:171], v[102:103] op_sel_hi:[0,1]
	v_pk_mul_f32 v[106:107], v[172:173], v[108:109] op_sel_hi:[0,1]
	v_pk_mul_f32 v[108:109], v[172:173], v[110:111] op_sel_hi:[0,1]
	v_pk_mul_f32 v[110:111], v[172:173], v[112:113] op_sel_hi:[0,1]
	v_pk_mul_f32 v[112:113], v[172:173], v[114:115] op_sel_hi:[0,1]
	v_pk_mul_f32 v[114:115], v[172:173], v[116:117] op_sel_hi:[0,1]
	v_pk_mul_f32 v[116:117], v[172:173], v[120:121] op_sel_hi:[0,1]
	v_pk_mul_f32 v[120:121], v[172:173], v[122:123] op_sel_hi:[0,1]
	v_pk_mul_f32 v[118:119], v[172:173], v[118:119] op_sel_hi:[0,1]
	v_pk_mul_f32 v[122:123], v[174:175], v[124:125] op_sel_hi:[0,1]
	v_pk_mul_f32 v[124:125], v[174:175], v[126:127] op_sel_hi:[0,1]
	v_pk_mul_f32 v[126:127], v[174:175], v[128:129] op_sel_hi:[0,1]
	v_pk_mul_f32 v[128:129], v[174:175], v[130:131] op_sel_hi:[0,1]
	v_pk_mul_f32 v[130:131], v[174:175], v[132:133] op_sel_hi:[0,1]
	v_pk_mul_f32 v[132:133], v[174:175], v[136:137] op_sel_hi:[0,1]
	v_pk_mul_f32 v[136:137], v[174:175], v[138:139] op_sel_hi:[0,1]
	v_pk_mul_f32 v[134:135], v[174:175], v[134:135] op_sel_hi:[0,1]
	v_pk_mul_f32 v[138:139], v[176:177], v[140:141] op_sel_hi:[0,1]
; #define GAS __attribute__((address_space(1)))
; template <int MODE, bool XBF>
; __device__ __forceinline__ void rmsnorm_rows(const void* x, const float* gain, bf16_t* H, int gw, int NGW, int lane, const LAS float* WF, const float* fbias, float* LF) {
;     ...
;             for (int j = 0; j < 2; ++j) { v[r][j][0] = v[r][j][0] * rstd * g[j][0]; v[r][j][1] = v[r][j][1] * rstd * g[j][1];
;                 *(GAS u32x4*)(H + hrow * D + 512 * j + lane * 8) = pack8(v[r][j][0], v[r][j][1]); }
	v_pk_mul_f32 v[140:141], v[176:177], v[142:143] op_sel_hi:[0,1]
	v_pk_mul_f32 v[142:143], v[176:177], v[144:145] op_sel_hi:[0,1]
	v_pk_mul_f32 v[144:145], v[176:177], v[146:147] op_sel_hi:[0,1]
	v_pk_mul_f32 v[146:147], v[176:177], v[148:149] op_sel_hi:[0,1]
	v_pk_mul_f32 v[148:149], v[176:177], v[152:153] op_sel_hi:[0,1]
	v_pk_mul_f32 v[152:153], v[176:177], v[154:155] op_sel_hi:[0,1]
	v_pk_mul_f32 v[150:151], v[176:177], v[150:151] op_sel_hi:[0,1]
	v_pk_mul_f32 v[30:31], v[6:7], v[30:31]
	v_pk_mul_f32 v[18:19], v[4:5], v[18:19]
	v_pk_mul_f32 v[34:35], v[2:3], v[34:35]
	v_pk_mul_f32 v[32:33], v[0:1], v[32:33]
	v_pk_mul_f32 v[40:41], v[14:15], v[40:41]
	v_pk_mul_f32 v[36:37], v[12:13], v[36:37]
	v_pk_mul_f32 v[154:155], v[10:11], v[20:21]
	v_pk_mul_f32 v[42:43], v[8:9], v[42:43]
	v_pk_mul_f32 v[44:45], v[6:7], v[44:45]
	v_pk_mul_f32 v[38:39], v[4:5], v[38:39]
	v_pk_mul_f32 v[48:49], v[2:3], v[48:49]
	v_pk_mul_f32 v[46:47], v[0:1], v[46:47]
	v_pk_mul_f32 v[52:53], v[14:15], v[52:53]
	v_pk_mul_f32 v[50:51], v[12:13], v[50:51]
	v_pk_mul_f32 v[54:55], v[10:11], v[54:55]
	v_pk_mul_f32 v[56:57], v[8:9], v[56:57]
	v_pk_mul_f32 v[60:61], v[6:7], v[60:61]
	v_pk_mul_f32 v[58:59], v[4:5], v[58:59]
	v_pk_mul_f32 v[64:65], v[2:3], v[64:65]
	v_pk_mul_f32 v[62:63], v[0:1], v[62:63]
	v_pk_mul_f32 v[68:69], v[14:15], v[68:69]
	v_pk_mul_f32 v[66:67], v[12:13], v[66:67]
	v_pk_mul_f32 v[70:71], v[10:11], v[70:71]
	v_pk_mul_f32 v[72:73], v[8:9], v[72:73]
	v_pk_mul_f32 v[76:77], v[6:7], v[76:77]
	v_pk_mul_f32 v[74:75], v[4:5], v[74:75]
	v_pk_mul_f32 v[80:81], v[2:3], v[80:81]
	v_pk_mul_f32 v[78:79], v[0:1], v[78:79]
	v_pk_mul_f32 v[84:85], v[14:15], v[84:85]
	v_pk_mul_f32 v[82:83], v[12:13], v[82:83]
	v_pk_mul_f32 v[86:87], v[10:11], v[86:87]
	v_pk_mul_f32 v[88:89], v[8:9], v[88:89]
	v_pk_mul_f32 v[92:93], v[6:7], v[92:93]
	v_pk_mul_f32 v[90:91], v[4:5], v[90:91]
	v_pk_mul_f32 v[96:97], v[2:3], v[96:97]
	v_pk_mul_f32 v[94:95], v[0:1], v[94:95]
	v_pk_mul_f32 v[100:101], v[14:15], v[100:101]
	v_pk_mul_f32 v[98:99], v[12:13], v[98:99]
	v_pk_mul_f32 v[102:103], v[10:11], v[102:103]
	v_pk_mul_f32 v[104:105], v[8:9], v[104:105]
	v_pk_mul_f32 v[108:109], v[6:7], v[108:109]
	v_pk_mul_f32 v[106:107], v[4:5], v[106:107]
	v_pk_mul_f32 v[112:113], v[2:3], v[112:113]
	v_pk_mul_f32 v[110:111], v[0:1], v[110:111]
	v_pk_mul_f32 v[116:117], v[14:15], v[116:117]
	v_pk_mul_f32 v[114:115], v[12:13], v[114:115]
	v_pk_mul_f32 v[118:119], v[10:11], v[118:119]
	v_pk_mul_f32 v[120:121], v[8:9], v[120:121]
	v_pk_mul_f32 v[124:125], v[6:7], v[124:125]
	v_pk_mul_f32 v[122:123], v[4:5], v[122:123]
	v_pk_mul_f32 v[128:129], v[2:3], v[128:129]
	v_pk_mul_f32 v[126:127], v[0:1], v[126:127]
	v_pk_mul_f32 v[132:133], v[14:15], v[132:133]
	v_pk_mul_f32 v[130:131], v[12:13], v[130:131]
	v_pk_mul_f32 v[134:135], v[10:11], v[134:135]
	v_pk_mul_f32 v[136:137], v[8:9], v[136:137]
	v_pk_mul_f32 v[140:141], v[6:7], v[140:141]
	v_pk_mul_f32 v[138:139], v[4:5], v[138:139]
	v_pk_mul_f32 v[144:145], v[2:3], v[144:145]
	v_pk_mul_f32 v[142:143], v[0:1], v[142:143]
	v_pk_mul_f32 v[148:149], v[14:15], v[148:149]
	v_pk_mul_f32 v[146:147], v[12:13], v[146:147]
	v_pk_mul_f32 v[150:151], v[10:11], v[150:151]
	v_pk_mul_f32 v[152:153], v[8:9], v[152:153]
	v_cvt_pk_bf16_f32 v18, v18, v19
	v_cvt_pk_bf16_f32 v19, v30, v31
	v_cvt_pk_bf16_f32 v20, v32, v33
	v_cvt_pk_bf16_f32 v21, v34, v35
	v_cvt_pk_bf16_f32 v30, v36, v37
	v_cvt_pk_bf16_f32 v31, v40, v41
	v_cvt_pk_bf16_f32 v32, v42, v43
	v_cvt_pk_bf16_f32 v33, v154, v155
	v_cvt_pk_bf16_f32 v34, v38, v39
	v_cvt_pk_bf16_f32 v35, v44, v45
	v_cvt_pk_bf16_f32 v36, v46, v47
	v_cvt_pk_bf16_f32 v37, v48, v49
	v_cvt_pk_bf16_f32 v38, v50, v51
	v_cvt_pk_bf16_f32 v39, v52, v53
	v_cvt_pk_bf16_f32 v40, v56, v57
	v_cvt_pk_bf16_f32 v41, v54, v55
	v_cvt_pk_bf16_f32 v42, v58, v59
	v_cvt_pk_bf16_f32 v43, v60, v61
	v_cvt_pk_bf16_f32 v44, v62, v63
	v_cvt_pk_bf16_f32 v45, v64, v65
	v_cvt_pk_bf16_f32 v46, v66, v67
	v_cvt_pk_bf16_f32 v47, v68, v69
	v_cvt_pk_bf16_f32 v48, v72, v73
	v_cvt_pk_bf16_f32 v49, v70, v71
	v_cvt_pk_bf16_f32 v50, v74, v75
	v_cvt_pk_bf16_f32 v51, v76, v77
	v_cvt_pk_bf16_f32 v52, v78, v79
	v_cvt_pk_bf16_f32 v53, v80, v81
	v_cvt_pk_bf16_f32 v54, v82, v83
	v_cvt_pk_bf16_f32 v55, v84, v85
	v_cvt_pk_bf16_f32 v56, v88, v89
	v_cvt_pk_bf16_f32 v57, v86, v87
	v_cvt_pk_bf16_f32 v58, v90, v91
	v_cvt_pk_bf16_f32 v59, v92, v93
	v_cvt_pk_bf16_f32 v60, v94, v95
	v_cvt_pk_bf16_f32 v61, v96, v97
	v_cvt_pk_bf16_f32 v62, v98, v99
	v_cvt_pk_bf16_f32 v63, v100, v101
	v_cvt_pk_bf16_f32 v64, v104, v105
	v_cvt_pk_bf16_f32 v65, v102, v103
	v_cvt_pk_bf16_f32 v66, v106, v107
	v_cvt_pk_bf16_f32 v67, v108, v109
	v_cvt_pk_bf16_f32 v68, v110, v111
	v_cvt_pk_bf16_f32 v69, v112, v113
	v_cvt_pk_bf16_f32 v70, v114, v115
	v_cvt_pk_bf16_f32 v71, v116, v117
	v_cvt_pk_bf16_f32 v72, v120, v121
	v_cvt_pk_bf16_f32 v73, v118, v119
	v_cvt_pk_bf16_f32 v74, v122, v123
	v_cvt_pk_bf16_f32 v75, v124, v125
	v_cvt_pk_bf16_f32 v76, v126, v127
	v_cvt_pk_bf16_f32 v77, v128, v129
	v_cvt_pk_bf16_f32 v78, v130, v131
	v_cvt_pk_bf16_f32 v79, v132, v133
	v_cvt_pk_bf16_f32 v80, v136, v137
	v_cvt_pk_bf16_f32 v81, v134, v135
	v_cvt_pk_bf16_f32 v82, v138, v139
	v_cvt_pk_bf16_f32 v83, v140, v141
	v_cvt_pk_bf16_f32 v84, v142, v143
	v_cvt_pk_bf16_f32 v85, v144, v145
	v_cvt_pk_bf16_f32 v86, v146, v147
	v_cvt_pk_bf16_f32 v87, v148, v149
	v_cvt_pk_bf16_f32 v88, v152, v153
	v_cvt_pk_bf16_f32 v89, v150, v151
	global_store_dwordx4 v[24:25], v[18:21], off
	global_store_dwordx4 v[24:25], v[30:33], off offset:1024
	global_store_dwordx4 v[24:25], v[34:37], off offset:2048
	global_store_dwordx4 v[24:25], v[38:41], off offset:3072
	global_store_dwordx4 v[26:27], v[42:45], off offset:-4096
	global_store_dwordx4 v[28:29], v[46:49], off offset:1024
	global_store_dwordx4 v[28:29], v[50:53], off offset:2048
	global_store_dwordx4 v[28:29], v[54:57], off offset:3072
	global_store_dwordx4 v[26:27], v[58:61], off
	global_store_dwordx4 v[26:27], v[62:65], off offset:1024
	global_store_dwordx4 v[26:27], v[66:69], off offset:2048
	global_store_dwordx4 v[26:27], v[70:73], off offset:3072
	global_store_dwordx4 v[24:25], v[74:77], off offset:-4096
	global_store_dwordx4 v[22:23], v[78:81], off offset:1024
	global_store_dwordx4 v[22:23], v[82:85], off offset:2048
	global_store_dwordx4 v[22:23], v[86:89], off offset:3072
	s_cbranch_scc1 .LBB0_421
